# attention epilogue: bf16 rounding via v_cvt_pk_bf16_f32 on pairs instead of the bit-16/add3 trick (5 instead of 8 instructions per pair)
# speedup vs baseline: 1.0087x; 1.0028x over previous
.LBB0_303:
	s_cmpk_gt_u32 s65, 0xff
	s_waitcnt lgkmcnt(0)
	s_barrier
	s_cbranch_scc1 .LBB0_275
	s_mulk_i32 s64, 0x2200
	s_add_i32 s34, s64, 0
	s_add_i32 s34, s34, 0x10000
	ds_read2st64_b32 v[130:131], v71 offset1:1
	ds_read2st64_b32 v[132:133], v71 offset0:2 offset1:3
	ds_read2st64_b32 v[134:135], v71 offset0:4 offset1:5
	ds_read2st64_b32 v[136:137], v71 offset0:6 offset1:7
	ds_read2st64_b32 v[138:139], v71 offset0:8 offset1:9
	ds_read2st64_b32 v[140:141], v71 offset0:10 offset1:11
	ds_read2st64_b32 v[142:143], v71 offset0:12 offset1:13
	ds_read2st64_b32 v[144:145], v71 offset0:14 offset1:15
	ds_read2st64_b32 v[146:147], v71 offset0:16 offset1:17
	ds_read2st64_b32 v[148:149], v71 offset0:18 offset1:19
	ds_read2st64_b32 v[150:151], v71 offset0:20 offset1:21
	ds_read2st64_b32 v[172:173], v71 offset0:22 offset1:23
	ds_read2st64_b32 v[174:175], v71 offset0:24 offset1:25
	ds_read2st64_b32 v[176:177], v71 offset0:26 offset1:27
	ds_read2st64_b32 v[178:179], v71 offset0:28 offset1:29
	ds_read2st64_b32 v[180:181], v71 offset0:30 offset1:31
	ds_read2st64_b32 v[182:183], v71 offset0:32 offset1:33
	ds_read2st64_b32 v[184:185], v71 offset0:34 offset1:35
	ds_read2st64_b32 v[186:187], v71 offset0:36 offset1:37
	ds_read2st64_b32 v[188:189], v71 offset0:38 offset1:39
	ds_read2st64_b32 v[190:191], v71 offset0:40 offset1:41
	ds_read2st64_b32 v[192:193], v71 offset0:42 offset1:43
	ds_read2st64_b32 v[194:195], v71 offset0:44 offset1:45
	ds_read2st64_b32 v[196:197], v71 offset0:46 offset1:47
	ds_read2st64_b32 v[198:199], v71 offset0:48 offset1:49
	ds_read2st64_b32 v[200:201], v71 offset0:50 offset1:51
	ds_read2st64_b32 v[202:203], v71 offset0:52 offset1:53
	ds_read2st64_b32 v[204:205], v71 offset0:54 offset1:55
	ds_read2st64_b32 v[206:207], v71 offset0:56 offset1:57
	ds_read2st64_b32 v[208:209], v71 offset0:58 offset1:59
	ds_read2st64_b32 v[210:211], v71 offset0:60 offset1:61
	ds_read2st64_b32 v[212:213], v71 offset0:62 offset1:63
	s_waitcnt lgkmcnt(15)
	v_sub_f32_e32 v60, v72, v130
	v_sub_f32_e32 v55, v0, v131
	v_sub_f32_e32 v52, v73, v132
	v_sub_f32_e32 v47, v74, v133
	v_sub_f32_e32 v44, v3, v134
	v_sub_f32_e32 v39, v36, v135
	v_sub_f32_e32 v28, v23, v138
	v_sub_f32_e32 v23, v38, v139
	v_sub_f32_e32 v36, v20, v136
	v_sub_f32_e32 v31, v6, v137
	v_sub_f32_e32 v20, v41, v140
	v_sub_f32_e32 v15, v26, v141
	v_sub_f32_e32 v12, v54, v142
	v_sub_f32_e32 v6, v77, v143
	v_sub_f32_e32 v3, v57, v144
	v_sub_f32_e32 v0, v14, v145
	v_sub_f32_e32 v62, v68, v146
	v_sub_f32_e32 v57, v49, v147
	v_sub_f32_e32 v54, v1, v148
	v_sub_f32_e32 v49, v18, v149
	v_sub_f32_e32 v46, v34, v150
	v_sub_f32_e32 v41, v51, v151
	v_sub_f32_e32 v38, v5, v172
	v_sub_f32_e32 v34, v22, v173
	v_sub_f32_e32 v30, v40, v174
	v_sub_f32_e32 v26, v56, v175
	v_sub_f32_e32 v22, v75, v176
	v_sub_f32_e32 v18, v10, v177
	v_sub_f32_e32 v14, v27, v178
	v_sub_f32_e32 v10, v59, v179
	v_sub_f32_e32 v5, v43, v180
	v_sub_f32_e32 v1, v76, v181
	v_sub_f32_e32 v74, v16, v182
	v_sub_f32_e32 v59, v32, v183
	s_waitcnt lgkmcnt(14)
	v_sub_f32_e32 v56, v48, v184
	v_sub_f32_e32 v51, v2, v185
	s_waitcnt lgkmcnt(13)
	v_sub_f32_e32 v48, v19, v186
	v_sub_f32_e32 v43, v53, v187
	s_waitcnt lgkmcnt(12)
	v_sub_f32_e32 v40, v35, v188
	v_sub_f32_e32 v35, v69, v189
	s_waitcnt lgkmcnt(11)
	v_sub_f32_e32 v32, v7, v190
	v_sub_f32_e32 v27, v24, v191
	s_waitcnt lgkmcnt(10)
	v_sub_f32_e32 v24, v42, v192
	v_sub_f32_e32 v19, v58, v193
	s_waitcnt lgkmcnt(9)
	v_sub_f32_e32 v16, v11, v194
	v_sub_f32_e32 v11, v29, v195
	s_waitcnt lgkmcnt(8)
	v_sub_f32_e32 v7, v45, v196
	v_sub_f32_e32 v2, v61, v197
	s_waitcnt lgkmcnt(7)
	v_sub_f32_e32 v72, v64, v198
	v_sub_f32_e32 v61, v17, v199
	s_waitcnt lgkmcnt(6)
	v_sub_f32_e32 v58, v33, v200
	v_sub_f32_e32 v53, v50, v201
	s_waitcnt lgkmcnt(5)
	v_sub_f32_e32 v50, v4, v202
	v_sub_f32_e32 v45, v21, v203
	s_waitcnt lgkmcnt(4)
	v_sub_f32_e32 v42, v37, v204
	v_sub_f32_e32 v37, v65, v205
	s_waitcnt lgkmcnt(3)
	v_sub_f32_e32 v33, v8, v206
	v_sub_f32_e32 v29, v9, v207
	s_waitcnt lgkmcnt(2)
	v_sub_f32_e32 v25, v25, v208
	v_sub_f32_e32 v21, v66, v209
	s_waitcnt lgkmcnt(0)
	v_sub_f32_e32 v4, v63, v213
	v_sub_f32_e32 v13, v13, v211
	v_sub_f32_e32 v9, v70, v212
	v_sub_f32_e32 v17, v67, v210
	s_waitcnt lgkmcnt(0)
	v_mul_f32_e32 v130, v62, v62
	v_fmac_f32_e32 v130, v60, v60
	v_fmac_f32_e32 v130, v74, v74
	v_fmac_f32_e32 v130, v72, v72
	v_mul_f32_e32 v131, v57, v57
	v_fmac_f32_e32 v131, v55, v55
	v_fmac_f32_e32 v131, v59, v59
	v_fmac_f32_e32 v131, v61, v61
	v_mul_f32_e32 v132, v54, v54
	v_fmac_f32_e32 v132, v52, v52
	v_fmac_f32_e32 v132, v56, v56
	v_fmac_f32_e32 v132, v58, v58
	v_mul_f32_e32 v133, v49, v49
	v_fmac_f32_e32 v133, v47, v47
	v_fmac_f32_e32 v133, v51, v51
	v_fmac_f32_e32 v133, v53, v53
	v_mul_f32_e32 v134, v46, v46
	v_fmac_f32_e32 v134, v44, v44
	v_fmac_f32_e32 v134, v48, v48
	v_fmac_f32_e32 v134, v50, v50
	v_mul_f32_e32 v135, v41, v41
	v_fmac_f32_e32 v135, v39, v39
	v_fmac_f32_e32 v135, v43, v43
	v_fmac_f32_e32 v135, v45, v45
	v_mul_f32_e32 v136, v38, v38
	v_fmac_f32_e32 v136, v36, v36
	v_fmac_f32_e32 v136, v40, v40
	v_fmac_f32_e32 v136, v42, v42
	v_mul_f32_e32 v137, v34, v34
	v_fmac_f32_e32 v137, v31, v31
	v_fmac_f32_e32 v137, v35, v35
	v_fmac_f32_e32 v137, v37, v37
	v_mul_f32_e32 v138, v30, v30
	v_fmac_f32_e32 v138, v28, v28
	v_fmac_f32_e32 v138, v32, v32
	v_fmac_f32_e32 v138, v33, v33
	v_mul_f32_e32 v139, v26, v26
	v_fmac_f32_e32 v139, v23, v23
	v_fmac_f32_e32 v139, v27, v27
	v_fmac_f32_e32 v139, v29, v29
	v_mul_f32_e32 v140, v22, v22
	v_fmac_f32_e32 v140, v20, v20
	v_fmac_f32_e32 v140, v24, v24
	v_fmac_f32_e32 v140, v25, v25
	v_mul_f32_e32 v141, v18, v18
	v_fmac_f32_e32 v141, v15, v15
	v_fmac_f32_e32 v141, v19, v19
	v_fmac_f32_e32 v141, v21, v21
	v_mul_f32_e32 v142, v14, v14
	v_fmac_f32_e32 v142, v12, v12
	v_fmac_f32_e32 v142, v16, v16
	v_fmac_f32_e32 v142, v17, v17
	v_mul_f32_e32 v143, v10, v10
	v_fmac_f32_e32 v143, v6, v6
	v_fmac_f32_e32 v143, v11, v11
	v_fmac_f32_e32 v143, v13, v13
	v_mul_f32_e32 v144, v5, v5
	v_fmac_f32_e32 v144, v3, v3
	v_fmac_f32_e32 v144, v7, v7
	v_fmac_f32_e32 v144, v9, v9
	v_mul_f32_e32 v145, v1, v1
	v_fmac_f32_e32 v145, v0, v0
	v_fmac_f32_e32 v145, v2, v2
	v_fmac_f32_e32 v145, v4, v4
	v_add_f32_dpp v130, v130, v130 quad_perm:[1,0,3,2] row_mask:0xf bank_mask:0xf
	v_add_f32_dpp v131, v131, v131 quad_perm:[1,0,3,2] row_mask:0xf bank_mask:0xf
	v_add_f32_dpp v132, v132, v132 quad_perm:[1,0,3,2] row_mask:0xf bank_mask:0xf
	v_add_f32_dpp v133, v133, v133 quad_perm:[1,0,3,2] row_mask:0xf bank_mask:0xf
	v_add_f32_dpp v134, v134, v134 quad_perm:[1,0,3,2] row_mask:0xf bank_mask:0xf
	v_add_f32_dpp v135, v135, v135 quad_perm:[1,0,3,2] row_mask:0xf bank_mask:0xf
	v_add_f32_dpp v136, v136, v136 quad_perm:[1,0,3,2] row_mask:0xf bank_mask:0xf
	v_add_f32_dpp v137, v137, v137 quad_perm:[1,0,3,2] row_mask:0xf bank_mask:0xf
	v_add_f32_dpp v138, v138, v138 quad_perm:[1,0,3,2] row_mask:0xf bank_mask:0xf
	v_add_f32_dpp v139, v139, v139 quad_perm:[1,0,3,2] row_mask:0xf bank_mask:0xf
	v_add_f32_dpp v140, v140, v140 quad_perm:[1,0,3,2] row_mask:0xf bank_mask:0xf
	v_add_f32_dpp v141, v141, v141 quad_perm:[1,0,3,2] row_mask:0xf bank_mask:0xf
	v_add_f32_dpp v142, v142, v142 quad_perm:[1,0,3,2] row_mask:0xf bank_mask:0xf
	v_add_f32_dpp v143, v143, v143 quad_perm:[1,0,3,2] row_mask:0xf bank_mask:0xf
	v_add_f32_dpp v144, v144, v144 quad_perm:[1,0,3,2] row_mask:0xf bank_mask:0xf
	v_add_f32_dpp v145, v145, v145 quad_perm:[1,0,3,2] row_mask:0xf bank_mask:0xf
	v_add_f32_dpp v130, v130, v130 quad_perm:[2,3,0,1] row_mask:0xf bank_mask:0xf
	v_add_f32_dpp v131, v131, v131 quad_perm:[2,3,0,1] row_mask:0xf bank_mask:0xf
	v_add_f32_dpp v132, v132, v132 quad_perm:[2,3,0,1] row_mask:0xf bank_mask:0xf
	v_add_f32_dpp v133, v133, v133 quad_perm:[2,3,0,1] row_mask:0xf bank_mask:0xf
	v_add_f32_dpp v134, v134, v134 quad_perm:[2,3,0,1] row_mask:0xf bank_mask:0xf
	v_add_f32_dpp v135, v135, v135 quad_perm:[2,3,0,1] row_mask:0xf bank_mask:0xf
	v_add_f32_dpp v136, v136, v136 quad_perm:[2,3,0,1] row_mask:0xf bank_mask:0xf
	v_add_f32_dpp v137, v137, v137 quad_perm:[2,3,0,1] row_mask:0xf bank_mask:0xf
	v_add_f32_dpp v138, v138, v138 quad_perm:[2,3,0,1] row_mask:0xf bank_mask:0xf
	v_add_f32_dpp v139, v139, v139 quad_perm:[2,3,0,1] row_mask:0xf bank_mask:0xf
	v_add_f32_dpp v140, v140, v140 quad_perm:[2,3,0,1] row_mask:0xf bank_mask:0xf
	v_add_f32_dpp v141, v141, v141 quad_perm:[2,3,0,1] row_mask:0xf bank_mask:0xf
	v_add_f32_dpp v142, v142, v142 quad_perm:[2,3,0,1] row_mask:0xf bank_mask:0xf
	v_add_f32_dpp v143, v143, v143 quad_perm:[2,3,0,1] row_mask:0xf bank_mask:0xf
	v_add_f32_dpp v144, v144, v144 quad_perm:[2,3,0,1] row_mask:0xf bank_mask:0xf
	v_add_f32_dpp v145, v145, v145 quad_perm:[2,3,0,1] row_mask:0xf bank_mask:0xf
	v_add_f32_dpp v130, v130, v130 row_half_mirror row_mask:0xf bank_mask:0xf
	v_add_f32_dpp v131, v131, v131 row_half_mirror row_mask:0xf bank_mask:0xf
	v_add_f32_dpp v132, v132, v132 row_half_mirror row_mask:0xf bank_mask:0xf
	v_add_f32_dpp v133, v133, v133 row_half_mirror row_mask:0xf bank_mask:0xf
	v_add_f32_dpp v134, v134, v134 row_half_mirror row_mask:0xf bank_mask:0xf
	v_add_f32_dpp v135, v135, v135 row_half_mirror row_mask:0xf bank_mask:0xf
	v_add_f32_dpp v136, v136, v136 row_half_mirror row_mask:0xf bank_mask:0xf
	v_add_f32_dpp v137, v137, v137 row_half_mirror row_mask:0xf bank_mask:0xf
	v_add_f32_dpp v138, v138, v138 row_half_mirror row_mask:0xf bank_mask:0xf
	v_add_f32_dpp v139, v139, v139 row_half_mirror row_mask:0xf bank_mask:0xf
	v_add_f32_dpp v140, v140, v140 row_half_mirror row_mask:0xf bank_mask:0xf
	v_add_f32_dpp v141, v141, v141 row_half_mirror row_mask:0xf bank_mask:0xf
	v_add_f32_dpp v142, v142, v142 row_half_mirror row_mask:0xf bank_mask:0xf
	v_add_f32_dpp v143, v143, v143 row_half_mirror row_mask:0xf bank_mask:0xf
	v_add_f32_dpp v144, v144, v144 row_half_mirror row_mask:0xf bank_mask:0xf
	v_add_f32_dpp v145, v145, v145 row_half_mirror row_mask:0xf bank_mask:0xf
	v_add_f32_dpp v130, v130, v130 row_mirror row_mask:0xf bank_mask:0xf
	v_add_f32_dpp v131, v131, v131 row_mirror row_mask:0xf bank_mask:0xf
	v_add_f32_dpp v132, v132, v132 row_mirror row_mask:0xf bank_mask:0xf
	v_add_f32_dpp v133, v133, v133 row_mirror row_mask:0xf bank_mask:0xf
	v_add_f32_dpp v134, v134, v134 row_mirror row_mask:0xf bank_mask:0xf
	v_add_f32_dpp v135, v135, v135 row_mirror row_mask:0xf bank_mask:0xf
	v_add_f32_dpp v136, v136, v136 row_mirror row_mask:0xf bank_mask:0xf
	v_add_f32_dpp v137, v137, v137 row_mirror row_mask:0xf bank_mask:0xf
	v_add_f32_dpp v138, v138, v138 row_mirror row_mask:0xf bank_mask:0xf
	v_add_f32_dpp v139, v139, v139 row_mirror row_mask:0xf bank_mask:0xf
	v_add_f32_dpp v140, v140, v140 row_mirror row_mask:0xf bank_mask:0xf
	v_add_f32_dpp v141, v141, v141 row_mirror row_mask:0xf bank_mask:0xf
	v_add_f32_dpp v142, v142, v142 row_mirror row_mask:0xf bank_mask:0xf
	v_add_f32_dpp v143, v143, v143 row_mirror row_mask:0xf bank_mask:0xf
	v_add_f32_dpp v144, v144, v144 row_mirror row_mask:0xf bank_mask:0xf
	v_add_f32_dpp v145, v145, v145 row_mirror row_mask:0xf bank_mask:0xf
	ds_bpermute_b32 v146, v165, v130
	ds_bpermute_b32 v147, v165, v131
	ds_bpermute_b32 v148, v165, v132
	ds_bpermute_b32 v149, v165, v133
	ds_bpermute_b32 v150, v165, v134
	ds_bpermute_b32 v151, v165, v135
	ds_bpermute_b32 v172, v165, v136
	ds_bpermute_b32 v173, v165, v137
	ds_bpermute_b32 v174, v165, v138
	ds_bpermute_b32 v175, v165, v139
	ds_bpermute_b32 v176, v165, v140
	ds_bpermute_b32 v177, v165, v141
	ds_bpermute_b32 v178, v165, v142
	ds_bpermute_b32 v179, v165, v143
	ds_bpermute_b32 v180, v165, v144
	ds_bpermute_b32 v181, v165, v145
	s_waitcnt lgkmcnt(15)
	v_add_f32_e32 v130, v130, v146
	s_waitcnt lgkmcnt(14)
	v_add_f32_e32 v131, v131, v147
	s_waitcnt lgkmcnt(13)
	v_add_f32_e32 v132, v132, v148
	s_waitcnt lgkmcnt(12)
	v_add_f32_e32 v133, v133, v149
	s_waitcnt lgkmcnt(11)
	v_add_f32_e32 v134, v134, v150
	s_waitcnt lgkmcnt(10)
	v_add_f32_e32 v135, v135, v151
	s_waitcnt lgkmcnt(9)
	v_add_f32_e32 v136, v136, v172
	s_waitcnt lgkmcnt(8)
	v_add_f32_e32 v137, v137, v173
	s_waitcnt lgkmcnt(7)
	v_add_f32_e32 v138, v138, v174
	s_waitcnt lgkmcnt(6)
	v_add_f32_e32 v139, v139, v175
	s_waitcnt lgkmcnt(5)
	v_add_f32_e32 v140, v140, v176
	s_waitcnt lgkmcnt(4)
	v_add_f32_e32 v141, v141, v177
	s_waitcnt lgkmcnt(3)
	v_add_f32_e32 v142, v142, v178
	s_waitcnt lgkmcnt(2)
	v_add_f32_e32 v143, v143, v179
	s_waitcnt lgkmcnt(1)
	v_add_f32_e32 v144, v144, v180
	s_waitcnt lgkmcnt(0)
	v_add_f32_e32 v145, v145, v181
	v_fmamk_f32 v130, v130, 0x3c000000, v153
	v_fmamk_f32 v131, v131, 0x3c000000, v153
	v_fmamk_f32 v132, v132, 0x3c000000, v153
	v_fmamk_f32 v133, v133, 0x3c000000, v153
	v_fmamk_f32 v134, v134, 0x3c000000, v153
	v_fmamk_f32 v135, v135, 0x3c000000, v153
	v_fmamk_f32 v136, v136, 0x3c000000, v153
	v_fmamk_f32 v137, v137, 0x3c000000, v153
	v_fmamk_f32 v138, v138, 0x3c000000, v153
	v_fmamk_f32 v139, v139, 0x3c000000, v153
	v_fmamk_f32 v140, v140, 0x3c000000, v153
	v_fmamk_f32 v141, v141, 0x3c000000, v153
	v_fmamk_f32 v142, v142, 0x3c000000, v153
	v_fmamk_f32 v143, v143, 0x3c000000, v153
	v_fmamk_f32 v144, v144, 0x3c000000, v153
	v_fmamk_f32 v145, v145, 0x3c000000, v153
	v_rsq_f32_e32 v130, v130
	v_rsq_f32_e32 v131, v131
	v_rsq_f32_e32 v132, v132
	v_rsq_f32_e32 v133, v133
	v_rsq_f32_e32 v134, v134
	v_rsq_f32_e32 v135, v135
	v_rsq_f32_e32 v136, v136
	v_rsq_f32_e32 v137, v137
	v_rsq_f32_e32 v138, v138
	v_rsq_f32_e32 v139, v139
	v_rsq_f32_e32 v140, v140
	v_rsq_f32_e32 v141, v141
	v_rsq_f32_e32 v142, v142
	v_rsq_f32_e32 v143, v143
	v_rsq_f32_e32 v144, v144
	v_rsq_f32_e32 v145, v145
	v_lshlrev_b32_e32 v190, 1, v171
	v_mul_u32_u24_e32 v191, 0x440, v170
	v_add3_u32 v190, s34, v190, v191
	v_mul_f32_e32 v182, v60, v130
	v_mul_f32_e32 v183, v62, v130
	v_cvt_pk_bf16_f32 v182, v182, v183
	ds_write_b16 v190, v182
	ds_write_b16_d16_hi v190, v182 offset:64
	v_mul_f32_e32 v184, v74, v130
	v_mul_f32_e32 v185, v72, v130
	v_cvt_pk_bf16_f32 v184, v184, v185
	ds_write_b16 v190, v184 offset:128
	ds_write_b16_d16_hi v190, v184 offset:192
	v_mul_f32_e32 v182, v55, v131
	v_mul_f32_e32 v183, v57, v131
	v_cvt_pk_bf16_f32 v182, v182, v183
	ds_write_b16 v190, v182 offset:272
	ds_write_b16_d16_hi v190, v182 offset:336
	v_mul_f32_e32 v184, v59, v131
	v_mul_f32_e32 v185, v61, v131
	v_cvt_pk_bf16_f32 v184, v184, v185
	ds_write_b16 v190, v184 offset:400
	ds_write_b16_d16_hi v190, v184 offset:464
	v_mul_f32_e32 v182, v52, v132
	v_mul_f32_e32 v183, v54, v132
	v_cvt_pk_bf16_f32 v182, v182, v183
	ds_write_b16 v190, v182 offset:544
	ds_write_b16_d16_hi v190, v182 offset:608
	v_mul_f32_e32 v184, v56, v132
	v_mul_f32_e32 v185, v58, v132
	v_cvt_pk_bf16_f32 v184, v184, v185
	ds_write_b16 v190, v184 offset:672
	ds_write_b16_d16_hi v190, v184 offset:736
	v_mul_f32_e32 v182, v47, v133
	v_mul_f32_e32 v183, v49, v133
	v_cvt_pk_bf16_f32 v182, v182, v183
	ds_write_b16 v190, v182 offset:816
	ds_write_b16_d16_hi v190, v182 offset:880
	v_mul_f32_e32 v184, v51, v133
	v_mul_f32_e32 v185, v53, v133
	v_cvt_pk_bf16_f32 v184, v184, v185
	ds_write_b16 v190, v184 offset:944
	ds_write_b16_d16_hi v190, v184 offset:1008
	v_mul_f32_e32 v182, v44, v134
	v_mul_f32_e32 v183, v46, v134
	v_cvt_pk_bf16_f32 v182, v182, v183
	ds_write_b16 v190, v182 offset:2176
	ds_write_b16_d16_hi v190, v182 offset:2240
	v_mul_f32_e32 v184, v48, v134
	v_mul_f32_e32 v185, v50, v134
	v_cvt_pk_bf16_f32 v184, v184, v185
	ds_write_b16 v190, v184 offset:2304
	ds_write_b16_d16_hi v190, v184 offset:2368
	v_mul_f32_e32 v182, v39, v135
	v_mul_f32_e32 v183, v41, v135
	v_cvt_pk_bf16_f32 v182, v182, v183
	ds_write_b16 v190, v182 offset:2448
	ds_write_b16_d16_hi v190, v182 offset:2512
	v_mul_f32_e32 v184, v43, v135
	v_mul_f32_e32 v185, v45, v135
	v_cvt_pk_bf16_f32 v184, v184, v185
	ds_write_b16 v190, v184 offset:2576
	ds_write_b16_d16_hi v190, v184 offset:2640
	v_mul_f32_e32 v182, v36, v136
	v_mul_f32_e32 v183, v38, v136
	v_cvt_pk_bf16_f32 v182, v182, v183
	ds_write_b16 v190, v182 offset:2720
	ds_write_b16_d16_hi v190, v182 offset:2784
	v_mul_f32_e32 v184, v40, v136
	v_mul_f32_e32 v185, v42, v136
	v_cvt_pk_bf16_f32 v184, v184, v185
	ds_write_b16 v190, v184 offset:2848
	ds_write_b16_d16_hi v190, v184 offset:2912
	v_mul_f32_e32 v182, v31, v137
	v_mul_f32_e32 v183, v34, v137
	v_cvt_pk_bf16_f32 v182, v182, v183
	ds_write_b16 v190, v182 offset:2992
	ds_write_b16_d16_hi v190, v182 offset:3056
	v_mul_f32_e32 v184, v35, v137
	v_mul_f32_e32 v185, v37, v137
	v_cvt_pk_bf16_f32 v184, v184, v185
	ds_write_b16 v190, v184 offset:3120
	ds_write_b16_d16_hi v190, v184 offset:3184
	v_mul_f32_e32 v182, v28, v138
	v_mul_f32_e32 v183, v30, v138
	v_cvt_pk_bf16_f32 v182, v182, v183
	ds_write_b16 v190, v182 offset:4352
	ds_write_b16_d16_hi v190, v182 offset:4416
	v_mul_f32_e32 v184, v32, v138
	v_mul_f32_e32 v185, v33, v138
	v_cvt_pk_bf16_f32 v184, v184, v185
	ds_write_b16 v190, v184 offset:4480
	ds_write_b16_d16_hi v190, v184 offset:4544
	v_mul_f32_e32 v182, v23, v139
	v_mul_f32_e32 v183, v26, v139
	v_cvt_pk_bf16_f32 v182, v182, v183
	ds_write_b16 v190, v182 offset:4624
	ds_write_b16_d16_hi v190, v182 offset:4688
	v_mul_f32_e32 v184, v27, v139
	v_mul_f32_e32 v185, v29, v139
	v_cvt_pk_bf16_f32 v184, v184, v185
	ds_write_b16 v190, v184 offset:4752
	ds_write_b16_d16_hi v190, v184 offset:4816
	v_mul_f32_e32 v182, v20, v140
	v_mul_f32_e32 v183, v22, v140
	v_cvt_pk_bf16_f32 v182, v182, v183
	ds_write_b16 v190, v182 offset:4896
	ds_write_b16_d16_hi v190, v182 offset:4960
	v_mul_f32_e32 v184, v24, v140
	v_mul_f32_e32 v185, v25, v140
	v_cvt_pk_bf16_f32 v184, v184, v185
	ds_write_b16 v190, v184 offset:5024
	ds_write_b16_d16_hi v190, v184 offset:5088
	v_mul_f32_e32 v182, v15, v141
	v_mul_f32_e32 v183, v18, v141
	v_cvt_pk_bf16_f32 v182, v182, v183
	ds_write_b16 v190, v182 offset:5168
	ds_write_b16_d16_hi v190, v182 offset:5232
	v_mul_f32_e32 v184, v19, v141
	v_mul_f32_e32 v185, v21, v141
	v_cvt_pk_bf16_f32 v184, v184, v185
	ds_write_b16 v190, v184 offset:5296
	ds_write_b16_d16_hi v190, v184 offset:5360
	v_mul_f32_e32 v182, v12, v142
	v_mul_f32_e32 v183, v14, v142
	v_cvt_pk_bf16_f32 v182, v182, v183
	ds_write_b16 v190, v182 offset:6528
	ds_write_b16_d16_hi v190, v182 offset:6592
	v_mul_f32_e32 v184, v16, v142
	v_mul_f32_e32 v185, v17, v142
	v_cvt_pk_bf16_f32 v184, v184, v185
	ds_write_b16 v190, v184 offset:6656
	ds_write_b16_d16_hi v190, v184 offset:6720
	v_mul_f32_e32 v182, v6, v143
	v_mul_f32_e32 v183, v10, v143
	v_cvt_pk_bf16_f32 v182, v182, v183
	ds_write_b16 v190, v182 offset:6800
	ds_write_b16_d16_hi v190, v182 offset:6864
	v_mul_f32_e32 v184, v11, v143
	v_mul_f32_e32 v185, v13, v143
	v_cvt_pk_bf16_f32 v184, v184, v185
	ds_write_b16 v190, v184 offset:6928
	ds_write_b16_d16_hi v190, v184 offset:6992
	v_mul_f32_e32 v182, v3, v144
	v_mul_f32_e32 v183, v5, v144
	v_cvt_pk_bf16_f32 v182, v182, v183
	ds_write_b16 v190, v182 offset:7072
	ds_write_b16_d16_hi v190, v182 offset:7136
	v_mul_f32_e32 v184, v7, v144
	v_mul_f32_e32 v185, v9, v144
	v_cvt_pk_bf16_f32 v184, v184, v185
	ds_write_b16 v190, v184 offset:7200
	ds_write_b16_d16_hi v190, v184 offset:7264
	v_mul_f32_e32 v182, v0, v145
	v_mul_f32_e32 v183, v1, v145
	v_cvt_pk_bf16_f32 v182, v182, v183
	ds_write_b16 v190, v182 offset:7344
	ds_write_b16_d16_hi v190, v182 offset:7408
	v_mul_f32_e32 v184, v2, v145
	v_mul_f32_e32 v185, v4, v145
	v_cvt_pk_bf16_f32 v184, v184, v185
	ds_write_b16 v190, v184 offset:7472
	ds_write_b16_d16_hi v190, v184 offset:7536
	s_or_b32 s0, s40, s99
	s_mov_b32 s1, s41
	s_lshl_b64 s[0:1], s[0:1], 11
	v_lshlrev_b32_e32 v0, 1, v169
	v_lshrrev_b32_e32 v6, 4, v168
	v_and_b32_e32 v96, 0xf0, v0
	v_mul_u32_u24_e32 v0, 0x110, v6
	s_add_u32 s0, s92, s0
	v_add3_u32 v8, s34, v96, v0
	s_addc_u32 s1, s93, s1
	s_lshl_b32 s35, s98, 8
	s_add_u32 s0, s0, s35
	s_addc_u32 s1, s1, 0
	s_waitcnt lgkmcnt(0)
	ds_read_b128 v[132:135], v8
	ds_read_b128 v[136:139], v8 offset:1088
	ds_read_b128 v[140:143], v8 offset:2176
	ds_read_b128 v[144:147], v8 offset:3264
	ds_read_b128 v[148:151], v8 offset:4352
	ds_read_b128 v[172:175], v8 offset:5440
	ds_read_b128 v[176:179], v8 offset:6528
	ds_read_b128 v[180:183], v8 offset:7616
	v_lshl_add_u64 v[4:5], s[0:1], 0, v[96:97]
	v_lshlrev_b32_e32 v96, 11, v6
	v_lshl_add_u64 v[6:7], v[4:5], 0, v[96:97]
	s_waitcnt lgkmcnt(7)
	global_store_dwordx4 v[6:7], v[132:135], off sc0 sc1
	v_or_b32_e32 v6, 0x2000, v96
	v_mov_b32_e32 v7, v97
	v_lshl_add_u64 v[6:7], v[4:5], 0, v[6:7]
	s_waitcnt lgkmcnt(6)
	global_store_dwordx4 v[6:7], v[136:139], off sc0 sc1
	v_or_b32_e32 v6, 0x4000, v96
	v_mov_b32_e32 v7, v97
	v_lshl_add_u64 v[6:7], v[4:5], 0, v[6:7]
	s_waitcnt lgkmcnt(5)
	global_store_dwordx4 v[6:7], v[140:143], off sc0 sc1
	v_or_b32_e32 v6, 0x6000, v96
	v_mov_b32_e32 v7, v97
	v_lshl_add_u64 v[6:7], v[4:5], 0, v[6:7]
	s_waitcnt lgkmcnt(4)
	global_store_dwordx4 v[6:7], v[144:147], off sc0 sc1
	v_or_b32_e32 v6, 0x8000, v96
	v_mov_b32_e32 v7, v97
	v_lshl_add_u64 v[6:7], v[4:5], 0, v[6:7]
	s_waitcnt lgkmcnt(3)
	global_store_dwordx4 v[6:7], v[148:151], off sc0 sc1
	v_or_b32_e32 v6, 0xa000, v96
	v_mov_b32_e32 v7, v97
	v_lshl_add_u64 v[6:7], v[4:5], 0, v[6:7]
	s_waitcnt lgkmcnt(2)
	global_store_dwordx4 v[6:7], v[172:175], off sc0 sc1
	v_or_b32_e32 v6, 0xc000, v96
	v_mov_b32_e32 v7, v97
	v_lshl_add_u64 v[6:7], v[4:5], 0, v[6:7]
	s_waitcnt lgkmcnt(1)
	global_store_dwordx4 v[6:7], v[176:179], off sc0 sc1
	v_or_b32_e32 v96, 0xe000, v96
	v_lshl_add_u64 v[4:5], v[4:5], 0, v[96:97]
	s_waitcnt lgkmcnt(0)
	global_store_dwordx4 v[4:5], v[180:183], off sc0 sc1
	s_branch .LBB0_275
